# attention: loop bookkeeping issued under the last PV MFMAs; K fragments of the second tile of each pair prefetched right after the last PV MFMA; shorter loop head
# baseline (speedup 1.0000x reference)
.LBB0_509:
	v_exp_f32_e32 v82, v82
	v_exp_f32_e32 v83, v83
	v_exp_f32_e32 v84, v84
	v_exp_f32_e32 v85, v85
	v_exp_f32_e32 v86, v86
	v_exp_f32_e32 v87, v87
	v_exp_f32_e32 v88, v88
	v_exp_f32_e32 v89, v89
	s_waitcnt lgkmcnt(0)
	v_cvt_pk_bf16_f32 v174, v82, v83
	v_cvt_pk_bf16_f32 v175, v84, v85
	v_cvt_pk_bf16_f32 v176, v86, v87
	v_cvt_pk_bf16_f32 v177, v88, v89
	v_add_f32_e32 v190, v82, v83
	v_add_f32_e32 v191, v84, v85
	v_add_f32_e32 v192, v86, v87
	v_add_f32_e32 v193, v88, v89
	v_mfma_f32_32x32x16_bf16 v[50:65], v[126:129], v[174:177], v[50:65]
	v_exp_f32_e32 v90, v90
	v_exp_f32_e32 v91, v91
	v_add_f32_e32 v190, v190, v191
	v_add_f32_e32 v192, v192, v193
	v_mfma_f32_32x32x16_bf16 v[34:49], v[122:125], v[174:177], v[34:49]
	v_exp_f32_e32 v92, v92
	v_exp_f32_e32 v93, v93
	v_cvt_pk_bf16_f32 v178, v90, v91
	v_add_f32_e32 v191, v90, v91
	v_mfma_f32_32x32x16_bf16 v[18:33], v[118:121], v[174:177], v[18:33]
	v_exp_f32_e32 v94, v94
	v_exp_f32_e32 v95, v95
	v_cvt_pk_bf16_f32 v179, v92, v93
	v_add_f32_e32 v193, v92, v93
	v_mfma_f32_32x32x16_bf16 v[2:17], v[114:117], v[174:177], v[2:17]
	v_exp_f32_e32 v96, v96
	v_exp_f32_e32 v97, v97
	v_cvt_pk_bf16_f32 v180, v94, v95
	v_add_f32_e32 v190, v190, v191
	v_add_f32_e32 v191, v94, v95
	v_cvt_pk_bf16_f32 v181, v96, v97
	v_add_f32_e32 v192, v192, v193
	v_add_f32_e32 v193, v96, v97
	v_mfma_f32_32x32x16_bf16 v[50:65], v[110:113], v[178:181], v[50:65]
	v_xor_b32_e32 v172, 64, v156
	v_xor_b32_e32 v0, 0x60, v156
	ds_read_b128 v[82:85], v172
	ds_read_b128 v[86:89], v172 offset:4096
	ds_read_b128 v[90:93], v172 offset:8192
	ds_read_b128 v[94:97], v172 offset:12288
	v_exp_f32_e32 v66, v66
	v_exp_f32_e32 v67, v67
	v_mfma_f32_32x32x16_bf16 v[34:49], v[106:109], v[178:181], v[34:49]
	ds_read_b128 v[156:159], v0
	ds_read_b128 v[160:163], v0 offset:4096
	ds_read_b128 v[164:167], v0 offset:8192
	ds_read_b128 v[168:171], v0 offset:12288
	v_exp_f32_e32 v68, v68
	v_exp_f32_e32 v69, v69
	v_cvt_pk_bf16_f32 v182, v66, v67
	v_add_f32_e32 v190, v190, v191
	v_mfma_f32_32x32x16_bf16 v[18:33], v[102:105], v[178:181], v[18:33]
	v_exp_f32_e32 v70, v70
	v_exp_f32_e32 v71, v71
	v_cvt_pk_bf16_f32 v183, v68, v69
	v_add_f32_e32 v191, v66, v67
	v_add_f32_e32 v192, v192, v193
	v_mfma_f32_32x32x16_bf16 v[2:17], v[98:101], v[178:181], v[2:17]
	v_exp_f32_e32 v72, v72
	v_exp_f32_e32 v73, v73
	v_cvt_pk_bf16_f32 v184, v70, v71
	v_add_f32_e32 v193, v68, v69
	v_add_f32_e32 v190, v190, v191
	v_cvt_pk_bf16_f32 v185, v72, v73
	v_add_f32_e32 v191, v70, v71
	s_waitcnt lgkmcnt(0)
	v_mfma_f32_32x32x16_bf16 v[50:65], v[82:85], v[182:185], v[50:65]
	v_exp_f32_e32 v74, v74
	v_exp_f32_e32 v75, v75
	v_add_f32_e32 v192, v192, v193
	v_add_f32_e32 v193, v72, v73
	v_mfma_f32_32x32x16_bf16 v[34:49], v[86:89], v[182:185], v[34:49]
	v_exp_f32_e32 v76, v76
	v_exp_f32_e32 v77, v77
	v_cvt_pk_bf16_f32 v186, v74, v75
	v_add_f32_e32 v190, v190, v191
	v_mfma_f32_32x32x16_bf16 v[18:33], v[90:93], v[182:185], v[18:33]
	v_exp_f32_e32 v78, v78
	v_exp_f32_e32 v79, v79
	v_cvt_pk_bf16_f32 v187, v76, v77
	v_add_f32_e32 v191, v74, v75
	v_add_f32_e32 v192, v192, v193
	v_mfma_f32_32x32x16_bf16 v[2:17], v[94:97], v[182:185], v[2:17]
	v_exp_f32_e32 v80, v80
	v_exp_f32_e32 v81, v81
	v_cvt_pk_bf16_f32 v188, v78, v79
	v_add_f32_e32 v193, v76, v77
	v_add_f32_e32 v190, v190, v191
	v_cvt_pk_bf16_f32 v189, v80, v81
	v_add_f32_e32 v191, v78, v79
	v_add_f32_e32 v192, v192, v193
	v_mfma_f32_32x32x16_bf16 v[50:65], v[156:159], v[186:189], v[50:65]
	v_add_f32_e32 v193, v80, v81
	v_add_f32_e32 v190, v190, v191
	s_add_i32 s13, s27, 1
	s_cmp_lg_u32 s27, 3
	s_cselect_b32 s27, s13, 0
	s_addk_i32 s26, 0xff00
	s_add_i32 s24, s24, 1
	s_add_i32 s13, s21, s26
	s_sub_i32 s25, s25, 64
	s_add_i32 s23, s23, 64
	v_mfma_f32_32x32x16_bf16 v[34:49], v[160:163], v[186:189], v[34:49]
	v_add_f32_e32 v192, v192, v193
	v_lshl_add_u64 v[130:131], v[130:131], 0, s[56:57]
	v_lshl_add_u64 v[132:133], v[132:133], 0, s[56:57]
	v_mfma_f32_32x32x16_bf16 v[18:33], v[164:167], v[186:189], v[18:33]
	v_add_f32_e32 v190, v190, v192
	v_lshl_add_u64 v[152:153], v[152:153], 0, s[90:91]
	v_mfma_f32_32x32x16_bf16 v[2:17], v[168:171], v[186:189], v[2:17]
	v_add_f32_e32 v155, v155, v190
	s_cmpk_eq_i32 s13, 0xfc00
	s_cbranch_scc1 .LBB0_525
	s_bitcmp1_b32 s24, 0
	s_cbranch_scc0 .Latt_even_entry
	s_mul_i32 s13, s27, 0x6000
	v_add_u32_e32 v0, s13, v205
	v_add_u32_e32 v172, s13, v206
	ds_read_b128 v[174:177], v0
	ds_read_b128 v[190:193], v0 offset:4096
	v_add_u32_e32 v0, s13, v207
	ds_read_b128 v[178:181], v172
	ds_read_b128 v[194:197], v172 offset:4096
	v_add_u32_e32 v172, s13, v208
	ds_read_b128 v[182:185], v0
	ds_read_b128 v[198:201], v0 offset:4096
	ds_read_b128 v[186:189], v172
	ds_read_b128 v[220:223], v172 offset:4096
	s_branch .LBB0_514

.LBB0_511:
	s_bitcmp1_b32 s24, 0
	s_cbranch_scc1 .LBB0_514
.Latt_even_entry:
	s_waitcnt vmcnt(0) lgkmcnt(0)
	s_barrier
	s_cmp_lg_u32 s26, 0
	s_cbranch_scc1 .Latt_q_resident
	ds_read_b128 v[230:233], v209
	ds_read_b128 v[234:237], v209 offset:32
	ds_read_b128 v[242:245], v209 offset:64
	ds_read_b128 v[246:249], v209 offset:96
	v_mov_b32_e32 v238, s18
	ds_read_b32 v238, v238

.LBB0_514:
	s_cmp_gt_i32 s23, s86
	s_cbranch_scc1 .LBB0_510
	s_mul_i32 s13, s27, 0x6000
	s_add_i32 s13, s13, 0
	s_cmpk_gt_i32 s25, 0x70
	s_cselect_b64 vcc, -1, 0
	s_add_i32 s28, s13, 0x2000
	v_add_u32_e32 v156, s28, v205
	s_bitcmp1_b32 s24, 0
	s_cbranch_scc1 .Latt_k_prefetched
	v_add_u32_e32 v0, s13, v205
	v_add_u32_e32 v82, s13, v206
	v_add_u32_e32 v83, s13, v207
	v_add_u32_e32 v84, s13, v208
	ds_read_b128 v[174:177], v0
	ds_read_b128 v[190:193], v0 offset:4096
	ds_read_b128 v[178:181], v82
	ds_read_b128 v[194:197], v82 offset:4096
	ds_read_b128 v[182:185], v83
	ds_read_b128 v[198:201], v83 offset:4096
	ds_read_b128 v[186:189], v84
	ds_read_b128 v[220:223], v84 offset:4096
.Latt_k_prefetched:
	s_waitcnt lgkmcnt(8)
	v_cndmask_b32_e32 v157, 0, v238, vcc
	v_xor_b32_e32 v0, 32, v156
	v_sub_f32_e32 v66, v157, v154
	v_mov_b32_e32 v67, v66
	v_mov_b32_e32 v68, v66
	v_mov_b32_e32 v69, v66
	v_mov_b32_e32 v70, v66
	v_mov_b32_e32 v71, v66
	v_mov_b32_e32 v72, v66
	v_mov_b32_e32 v73, v66
	v_mov_b32_e32 v74, v66
	v_mov_b32_e32 v75, v66
	v_mov_b32_e32 v76, v66
	v_mov_b32_e32 v77, v66
	v_mov_b32_e32 v78, v66
	v_mov_b32_e32 v79, v66
	v_mov_b32_e32 v80, v66
	v_mov_b32_e32 v81, v66
	s_and_b64 vcc, exec, vcc
	s_nop 0
	s_waitcnt lgkmcnt(7)
	v_mfma_f32_32x32x16_bf16 v[82:97], v[174:177], v[230:233], v[66:81]
	s_waitcnt lgkmcnt(6)
	v_mfma_f32_32x32x16_bf16 v[66:81], v[190:193], v[230:233], v[66:81]
	ds_read_b128 v[126:129], v156
	ds_read_b128 v[122:125], v156 offset:4096
	s_waitcnt lgkmcnt(7)
	v_mfma_f32_32x32x16_bf16 v[82:97], v[178:181], v[234:237], v[82:97]
	s_waitcnt lgkmcnt(6)
	v_mfma_f32_32x32x16_bf16 v[66:81], v[194:197], v[234:237], v[66:81]
	ds_read_b128 v[118:121], v156 offset:8192
	ds_read_b128 v[114:117], v156 offset:12288
	s_waitcnt lgkmcnt(7)
	v_mfma_f32_32x32x16_bf16 v[82:97], v[182:185], v[242:245], v[82:97]
	s_waitcnt lgkmcnt(6)
	v_mfma_f32_32x32x16_bf16 v[66:81], v[198:201], v[242:245], v[66:81]
	ds_read_b128 v[110:113], v0
	ds_read_b128 v[106:109], v0 offset:4096
	s_waitcnt lgkmcnt(7)
	v_mfma_f32_32x32x16_bf16 v[82:97], v[186:189], v[246:249], v[82:97]
	s_waitcnt lgkmcnt(6)
	v_mfma_f32_32x32x16_bf16 v[66:81], v[220:223], v[246:249], v[66:81]
	ds_read_b128 v[102:105], v0 offset:8192
	ds_read_b128 v[98:101], v0 offset:12288
	s_cbranch_vccnz .LBB0_517
	v_add_u32_e32 v0, s26, v214
	v_add_u32_e32 v157, 0x18094, v0
	ds_read2_b32 v[158:159], v157 offset0:58 offset1:59
	ds_read2_b32 v[160:161], v157 offset0:26 offset1:27
	ds_read2_b32 v[162:163], v157 offset0:56 offset1:57
	ds_read2_b32 v[164:165], v157 offset0:24 offset1:25
	ds_read2_b32 v[166:167], v157 offset0:50 offset1:51
	ds_read2_b32 v[168:169], v157 offset0:18 offset1:19
	ds_read2_b32 v[174:175], v157 offset0:48 offset1:49
	ds_read2_b32 v[176:177], v157 offset0:16 offset1:17
	ds_read2_b32 v[178:179], v157 offset0:42 offset1:43
	ds_read2_b32 v[180:181], v157 offset0:10 offset1:11
	ds_read2_b32 v[182:183], v157 offset0:40 offset1:41
	ds_read2_b32 v[184:185], v157 offset0:8 offset1:9
	ds_read2_b32 v[190:191], v157 offset0:34 offset1:35
	ds_read2_b32 v[192:193], v157 offset0:2 offset1:3
	ds_read2_b32 v[194:195], v157 offset0:32 offset1:33
	ds_read2_b32 v[196:197], v157 offset0:0 offset1:1
	s_waitcnt lgkmcnt(0)
	v_pk_add_f32 v[82:83], v[82:83], v[158:159] op_sel:[0,1] op_sel_hi:[1,0]
	v_pk_add_f32 v[66:67], v[66:67], v[160:161] op_sel:[0,1] op_sel_hi:[1,0]
	v_pk_add_f32 v[84:85], v[84:85], v[162:163] op_sel:[0,1] op_sel_hi:[1,0]
	v_pk_add_f32 v[68:69], v[68:69], v[164:165] op_sel:[0,1] op_sel_hi:[1,0]
	v_pk_add_f32 v[86:87], v[86:87], v[166:167] op_sel:[0,1] op_sel_hi:[1,0]
	v_pk_add_f32 v[70:71], v[70:71], v[168:169] op_sel:[0,1] op_sel_hi:[1,0]
	v_pk_add_f32 v[88:89], v[88:89], v[174:175] op_sel:[0,1] op_sel_hi:[1,0]
	v_pk_add_f32 v[72:73], v[72:73], v[176:177] op_sel:[0,1] op_sel_hi:[1,0]
	v_pk_add_f32 v[90:91], v[90:91], v[178:179] op_sel:[0,1] op_sel_hi:[1,0]
	v_pk_add_f32 v[74:75], v[74:75], v[180:181] op_sel:[0,1] op_sel_hi:[1,0]
	v_pk_add_f32 v[92:93], v[92:93], v[182:183] op_sel:[0,1] op_sel_hi:[1,0]
	v_pk_add_f32 v[76:77], v[76:77], v[184:185] op_sel:[0,1] op_sel_hi:[1,0]
	v_pk_add_f32 v[94:95], v[94:95], v[190:191] op_sel:[0,1] op_sel_hi:[1,0]
	v_pk_add_f32 v[78:79], v[78:79], v[192:193] op_sel:[0,1] op_sel_hi:[1,0]
	v_pk_add_f32 v[96:97], v[96:97], v[194:195] op_sel:[0,1] op_sel_hi:[1,0]
	v_pk_add_f32 v[80:81], v[80:81], v[196:197] op_sel:[0,1] op_sel_hi:[1,0]

.LBB0_525:
	s_waitcnt lgkmcnt(0)
	v_mov_b32_e32 v0, v155
	s_nop 1
	v_permlane32_swap_b32_e32 v155, v0
	v_add_f32_e32 v0, v155, v0
	v_div_scale_f32 v66, s[24:25], v0, v0, 1.0
	v_rcp_f32_e32 v67, v66
	s_mov_b64 s[44:45], -1
	v_fma_f32 v68, -v66, v67, 1.0
	v_fmac_f32_e32 v67, v68, v67
	v_div_scale_f32 v68, vcc, 1.0, v0, 1.0
	v_mul_f32_e32 v69, v68, v67
	v_fma_f32 v70, -v66, v69, v68
	v_fmac_f32_e32 v69, v70, v67
	v_fma_f32 v66, -v66, v69, v68
	v_div_fmas_f32 v66, v66, v67, v69
	v_div_fixup_f32 v0, v66, v0, 1.0
	s_and_b64 vcc, exec, s[10:11]
	s_cbranch_vccnz .LBB0_527
	s_andn2_b64 vcc, exec, s[44:45]
	s_cbranch_vccnz .LBB0_503
	s_branch .LBB0_528
